# grid barrier: the leader issues its L1 invalidate after the XCD release, non-leaders right before their first poll
# speedup vs baseline: 1.0049x; 1.0049x over previous
.LBB0_143:
	s_or_b64 exec, exec, s[4:5]
	buffer_inv sc1
	s_waitcnt vmcnt(0)

.LBB0_705:
	s_or_b64 exec, exec, s[2:3]
	v_cvt_f32_u32_e32 v5, v3
	s_waitcnt vmcnt(0)
	v_readfirstlane_b32 s2, v4
	v_sub_u32_e32 v4, 0, v3
	v_rcp_iflag_f32_e32 v5, v5
	v_add_u32_e32 v6, s2, v1
	v_mul_f32_e32 v5, 0x4f7ffffe, v5
	v_cvt_u32_f32_e32 v5, v5
	v_mul_lo_u32 v1, v4, v5
	v_mul_hi_u32 v1, v5, v1
	v_add_u32_e32 v1, v5, v1
	v_mul_hi_u32 v1, v6, v1
	v_mul_lo_u32 v4, v1, v3
	v_sub_u32_e32 v4, v6, v4
	v_add_u32_e32 v5, 1, v1
	v_cmp_ge_u32_e32 vcc, v4, v3
	s_nop 1
	v_cndmask_b32_e32 v1, v1, v5, vcc
	v_sub_u32_e32 v5, v4, v3
	v_cndmask_b32_e32 v4, v4, v5, vcc
	v_add_u32_e32 v5, 1, v1
	v_cmp_ge_u32_e32 vcc, v4, v3
	v_add_u32_e32 v4, 1, v6
	s_nop 0
	v_cndmask_b32_e32 v1, v1, v5, vcc
	v_mul_lo_u32 v5, v3, v1
	v_add_u32_e32 v3, v5, v3
	v_cmp_ne_u32_e32 vcc, v4, v3
	s_and_saveexec_b64 s[2:3], vcc
	s_xor_b64 s[2:3], exec, s[2:3]
	s_cbranch_execz .LBB0_719
	v_readlane_b32 s4, v254, 54
	v_readlane_b32 s5, v254, 55
	s_waitcnt lgkmcnt(0)
	buffer_inv sc1
	s_nop 3
	global_load_dword v2, v0, s[4:5] sc1
	s_waitcnt vmcnt(0)
	v_cmp_eq_u32_e32 vcc, v2, v1
	s_and_saveexec_b64 s[4:5], vcc
	s_cbranch_execz .LBB0_718
	s_mov_b32 s17, 1
	s_mov_b64 s[6:7], 0
	s_branch .LBB0_709
